# attention: static s_setprio 1 for waves 4-7 during the attention phase
# baseline (speedup 1.0000x reference)
;     __device__ __forceinline__ unsigned char* ws() const { return (unsigned char*)(GAS unsigned char*)get(22); }
; __device__ __forceinline__ void attention_phase(const PT a, unsigned char* ws, int l, unsigned char* lds_generic, int tid, bool dry = false) {
;     using abf = attn_body::bf16;
;     const abf* Q = (const abf*)(ws + WS_Q); const abf* K = (const abf*)(ws + WS_K); const abf* V = (const abf*)(ws + WS_V); abf* O = dry ? (abf*)(ws + WS_END + MiB) : (abf*)(ws + WS_Q);
;     unsigned* ctr = (unsigned*)(ws + WS_CTL) + l + (dry ? 8 : 0);
;     volatile unsigned* slot = (volatile unsigned*)(lds_generic + MISC_OFF);
;     unsigned pre = 0u; if (tid == 0) pre = atomicAdd(ctr, 1u);
;     for (;;) {
;         if (tid == 0) { *slot = pre; pre = atomicAdd(ctr, 1u); }
;         __syncthreads();
;         const int idx = (int)__builtin_amdgcn_readfirstlane(*slot);
;         if (idx >= ATT_UNITS + NSTRIP) break;
.LBB0_858:
	s_or_b64 exec, exec, s[4:5]
	s_mov_b64 s[6:7], src_shared_base
	s_add_u32 s6, s0, 0xda00000
	s_addc_u32 s71, s1, 0
	s_add_u32 s72, s0, 0x13b00000
	s_addc_u32 s73, s1, 0
	s_add_u32 s74, s0, 0x15340000
	s_addc_u32 s75, s1, 0
	s_add_u32 s8, s0, 0x1cc80000
	s_addc_u32 s9, s1, 0
	s_add_u32 s10, s0, 0x15b50000
	s_addc_u32 s11, s1, 0
	s_add_u32 s76, s0, 0x14310000
	s_addc_u32 s77, s1, 0
	s_add_u32 s24, s0, 0x15348000
	s_addc_u32 s25, s1, 0
	s_add_u32 s78, s0, 0x13b08000
	s_addc_u32 s79, s1, 0
	s_add_i32 s80, 0, 0x20140
	v_mov_b32_e32 v193, 0
	s_movk_i32 s81, 0x810
	s_mov_b64 s[26:27], 0x8000
	s_movk_i32 s82, 0x80f
	s_mov_b64 s[28:29], 0x10000
	s_mov_b64 s[30:31], 0x18000
	v_readfirstlane_b32 s98, v190
	s_lshr_b32 s98, s98, 8
	s_cmp_eq_u32 s98, 0
	s_cbranch_scc1 .Lprio_skip0
	s_setprio 1
.Lprio_skip0:
	s_mov_b32 s83, 0x41000000
	s_mov_b64 s[34:35], 0x20000
	s_mov_b64 s[36:37], 0x100000
	s_mov_b64 s[38:39], 0xf0000
	s_mov_b64 s[40:41], 0xf8000
	s_movk_i32 s84, 0x1010
	s_movk_i32 s85, 0x100f
	s_mov_b64 s[42:43], 0x200000
	s_mov_b64 s[44:45], 0x1f0000
	s_mov_b64 s[46:47], 0x1f8000
	s_add_i32 s86, 0, 0x20448
	s_add_i32 s87, 0, 0x20450
	s_mov_b64 s[48:49], 0x1000
	s_mov_b64 s[50:51], 0x2000
	s_mov_b32 s88, 0xc140
	s_movk_i32 s89, 0x403f
	s_mov_b32 s90, 0x7f807f81
	s_mov_b64 s[52:53], 0x1cc80800
	s_mov_b64 s[54:55], 0x1cc81000
	s_branch .LBB0_862

;     __device__ __forceinline__ unsigned char* ws() const { return (unsigned char*)(GAS unsigned char*)get(22); }
; __device__ __forceinline__ void attention_phase(const PT a, unsigned char* ws, int l, unsigned char* lds_generic, int tid, bool dry = false) {
;     using abf = attn_body::bf16;
;     const abf* Q = (const abf*)(ws + WS_Q); const abf* K = (const abf*)(ws + WS_K); const abf* V = (const abf*)(ws + WS_V); abf* O = dry ? (abf*)(ws + WS_END + MiB) : (abf*)(ws + WS_Q);
;     unsigned* ctr = (unsigned*)(ws + WS_CTL) + l + (dry ? 8 : 0);
;     volatile unsigned* slot = (volatile unsigned*)(lds_generic + MISC_OFF);
;     unsigned pre = 0u; if (tid == 0) pre = atomicAdd(ctr, 1u);
;     for (;;) {
;         if (tid == 0) { *slot = pre; pre = atomicAdd(ctr, 1u); }
;         __syncthreads();
;         const int idx = (int)__builtin_amdgcn_readfirstlane(*slot);
;         if (idx >= ATT_UNITS + NSTRIP) break;
.LBB0_2457:
	s_or_b64 exec, exec, s[4:5]
	s_mov_b64 s[6:7], src_shared_base
	s_add_u32 s6, s0, 0xda00000
	s_addc_u32 s71, s1, 0
	s_add_u32 s72, s0, 0x13b00000
	s_addc_u32 s73, s1, 0
	s_add_u32 s74, s0, 0x15340000
	s_addc_u32 s75, s1, 0
	s_add_u32 s8, s0, 0x1cc80000
	s_addc_u32 s9, s1, 0
	s_add_u32 s10, s0, 0x15b50000
	s_addc_u32 s11, s1, 0
	s_add_u32 s76, s0, 0x14310000
	s_addc_u32 s77, s1, 0
	s_add_u32 s24, s0, 0x15348000
	s_addc_u32 s25, s1, 0
	s_add_u32 s78, s0, 0x13b08000
	s_addc_u32 s79, s1, 0
	s_add_i32 s80, 0, 0x20140
	v_mov_b32_e32 v193, 0
	s_movk_i32 s81, 0x810
	s_mov_b64 s[26:27], 0x8000
	s_mov_b64 s[28:29], 0x10000
	s_mov_b64 s[30:31], 0x18000
	v_readfirstlane_b32 s98, v190
	s_lshr_b32 s98, s98, 8
	s_cmp_eq_u32 s98, 0
	s_cbranch_scc1 .Lprio_skip1
	s_setprio 1
.Lprio_skip1:
	s_mov_b32 s82, 0x41000000
	s_mov_b64 s[34:35], 0x20000
	s_mov_b64 s[36:37], 0x100000
	s_movk_i32 s83, 0x1010
	s_mov_b64 s[38:39], 0x200000
	s_mov_b64 s[40:41], 0x1f0000
	s_mov_b64 s[42:43], 0x1f8000
	s_add_i32 s84, 0, 0x20448
	s_add_i32 s85, 0, 0x20450
	s_mov_b64 s[44:45], 0x3000
	s_mov_b64 s[46:47], 0x4000
	s_mov_b64 s[48:49], 0x5000
	s_mov_b64 s[50:51], 0x1000
	s_movk_i32 s86, 0x5000
	s_movk_i32 s87, 0x1000
	s_mov_b32 s88, 0xc140
	s_movk_i32 s89, 0x403f
	s_mov_b32 s90, 0x7f807f81
	s_mov_b64 s[52:53], 0x1cc80800
	s_mov_b64 s[54:55], 0x1cc81000
	s_branch .LBB0_2461

;     __device__ __forceinline__ unsigned char* ws() const { return (unsigned char*)(GAS unsigned char*)get(22); }
; __device__ __forceinline__ void attention_phase(const PT a, unsigned char* ws, int l, unsigned char* lds_generic, int tid, bool dry = false) {
;     using abf = attn_body::bf16;
;     const abf* Q = (const abf*)(ws + WS_Q); const abf* K = (const abf*)(ws + WS_K); const abf* V = (const abf*)(ws + WS_V); abf* O = dry ? (abf*)(ws + WS_END + MiB) : (abf*)(ws + WS_Q);
;     unsigned* ctr = (unsigned*)(ws + WS_CTL) + l + (dry ? 8 : 0);
;     volatile unsigned* slot = (volatile unsigned*)(lds_generic + MISC_OFF);
;     unsigned pre = 0u; if (tid == 0) pre = atomicAdd(ctr, 1u);
;     for (;;) {
;         if (tid == 0) { *slot = pre; pre = atomicAdd(ctr, 1u); }
;         __syncthreads();
;         const int idx = (int)__builtin_amdgcn_readfirstlane(*slot);
;         if (idx >= ATT_UNITS + NSTRIP) break;
.Lprio_skip2:
	s_mov_b32 s82, 0x41000000
	s_mov_b64 s[34:35], 0x20000
	s_mov_b64 s[36:37], 0x100000
	s_mov_b64 s[38:39], 0xf8000
	s_movk_i32 s83, 0x1010
	s_movk_i32 s84, 0x100f
	s_mov_b64 s[40:41], 0x200000
	s_mov_b64 s[42:43], 0x1f0000
	s_mov_b64 s[44:45], 0x1f8000
	s_add_i32 s85, 0, 0x20448
	s_add_i32 s86, 0, 0x20450
	s_mov_b64 s[46:47], 0x6000
	s_mov_b64 s[48:49], 0x7000
	s_mov_b64 s[50:51], 0x2000
	s_movk_i32 s87, 0x7000
	s_mov_b32 s88, 0xc140
	s_movk_i32 s89, 0x403f
	s_mov_b32 s90, 0x7f807f81
	s_mov_b64 s[52:53], 0x1cc80800
	s_mov_b64 s[54:55], 0x1cc81000
	s_branch .LBB0_4060

;     __device__ __forceinline__ unsigned char* ws() const { return (unsigned char*)(GAS unsigned char*)get(22); }
; __device__ __forceinline__ void attention_phase(const PT a, unsigned char* ws, int l, unsigned char* lds_generic, int tid, bool dry = false) {
;     using abf = attn_body::bf16;
;     const abf* Q = (const abf*)(ws + WS_Q); const abf* K = (const abf*)(ws + WS_K); const abf* V = (const abf*)(ws + WS_V); abf* O = dry ? (abf*)(ws + WS_END + MiB) : (abf*)(ws + WS_Q);
;     unsigned* ctr = (unsigned*)(ws + WS_CTL) + l + (dry ? 8 : 0);
;     volatile unsigned* slot = (volatile unsigned*)(lds_generic + MISC_OFF);
;     unsigned pre = 0u; if (tid == 0) pre = atomicAdd(ctr, 1u);
;     for (;;) {
;         if (tid == 0) { *slot = pre; pre = atomicAdd(ctr, 1u); }
;         __syncthreads();
;         const int idx = (int)__builtin_amdgcn_readfirstlane(*slot);
;         if (idx >= ATT_UNITS + NSTRIP) break;
.Lprio_skip3:
	s_mov_b32 s82, 0x41000000
	s_mov_b64 s[34:35], 0x20000
	s_mov_b64 s[36:37], 0x100000
	s_movk_i32 s83, 0x1010
	s_mov_b64 s[38:39], 0x200000
	s_mov_b64 s[40:41], 0x1f0000
	s_mov_b64 s[42:43], 0x1f8000
	s_add_i32 s84, 0, 0x20448
	s_add_i32 s85, 0, 0x20450
	s_mov_b64 s[44:45], 0x9000
	s_mov_b64 s[46:47], 0xa000
	s_mov_b64 s[48:49], 0xb000
	s_mov_b64 s[50:51], 0x3000
	s_mov_b32 s86, 0xb000
	s_movk_i32 s87, 0x3000
	s_mov_b32 s88, 0xc140
	s_movk_i32 s89, 0x403f
	s_mov_b32 s90, 0x7f807f81
	s_mov_b64 s[52:53], 0x1cc80800
	s_mov_b64 s[54:55], 0x1cc81000
	s_branch .LBB0_5517
